# speedup vs baseline: 1.0062x; 1.0027x over previous
; __device__ __forceinline__ unsigned cvt_pk_bf16(float lo, float hi) { const f32x2 v = {lo, hi}; const bf16v2 r = __builtin_convertvector(v, bf16v2); return __builtin_bit_cast(unsigned, r); }
; __device__ __forceinline__ int otid() { int t = threadIdx.x; asm volatile("" : "+v"(t)); return t; }
; __device__ __forceinline__ int obid() { int b = blockIdx.x; asm volatile("" : "+s"(b)); return b; }
; __device__ void norm_phase(const float* xp, const float* xs, float* out, const float* gain, bf16_t* H, float* SSo) {
;     const int lane = otid() & 63, gw = obid() * 8 + (otid() >> 6), nw = gridDim.x * 8;
;     for (int row = gw; row < T; row += nw) {
;         const float* xr = row < 8192 ? xp + (size_t)row * DM : xs + (size_t)(row - 8192) * DM;
;         f32x4 v[8]; float ss = 0.f;
; #pragma unroll
;         for (int j = 0; j < 8; ++j) { v[j] = *(const f32x4*)(xr + (lane + 64 * j) * 4); ss += v[j][0] * v[j][0] + v[j][1] * v[j][1] + v[j][2] * v[j][2] + v[j][3] * v[j][3]; }
; #pragma unroll
;         for (int o = 32; o >= 1; o >>= 1) ss += __shfl_xor(ss, o);
;         if (lane < 8) SSo[(size_t)lane * T + row] = lane == 0 ? ss : 0.f;
; #pragma unroll
;         for (int j = 0; j < 8; ++j) { const f32x4 g = *(const f32x4*)(gain + (lane + 64 * j) * 4);
;             u32x2 w; w.x = cvt_pk_bf16(v[j][0] * g[0], v[j][1] * g[1]); w.y = cvt_pk_bf16(v[j][2] * g[2], v[j][3] * g[3]);
;             *(u32x2*)(H + (size_t)row * DM + (lane + 64 * j) * 4) = w;
;             *(f32x4*)(out + (size_t)row * DM + (lane + 64 * j) * 4) = v[j]; }
;     }
; }
.LBB0_389:
	s_or_b64 exec, exec, s[6:7]
	v_readlane_b32 s6, v254, 28
	v_readlane_b32 s7, v254, 29
	v_lshl_add_u64 v[44:45], v[44:45], 0, s[90:91]
	s_waitcnt vmcnt(0)
	v_pk_mul_f32 v[84:85], v[4:5], v[102:103]
	v_pk_mul_f32 v[82:83], v[2:3], v[100:101]
	v_lshl_add_u64 v[46:47], v[46:47], 0, s[6:7]
	v_cvt_pk_bf16_f32 v82, v82, v83
	v_cvt_pk_bf16_f32 v83, v84, v85
	global_store_dwordx2 v[50:51], v[82:83], off offset:-2048
	s_movk_i32 s6, 0x5fff
	v_cmp_lt_i32_e64 s[38:39], s6, v44
	v_readlane_b32 s6, v254, 32
	v_readlane_b32 s7, v254, 33
	s_or_b64 s[4:5], s[38:39], s[4:5]
	v_pk_mul_f32 v[88:89], v[8:9], v[106:107]
	v_pk_mul_f32 v[86:87], v[6:7], v[104:105]
	s_nop 0
	v_cvt_pk_bf16_f32 v86, v86, v87
	v_cvt_pk_bf16_f32 v87, v88, v89
	global_store_dwordx2 v[50:51], v[86:87], off offset:-1536
	v_pk_mul_f32 v[84:85], v[12:13], v[110:111]
	v_pk_mul_f32 v[82:83], v[10:11], v[108:109]
	s_nop 0
	v_cvt_pk_bf16_f32 v82, v82, v83
	v_cvt_pk_bf16_f32 v83, v84, v85
	global_store_dwordx2 v[50:51], v[82:83], off offset:-1024
	v_pk_mul_f32 v[88:89], v[16:17], v[114:115]
	v_pk_mul_f32 v[86:87], v[14:15], v[112:113]
	s_nop 0
	v_cvt_pk_bf16_f32 v86, v86, v87
	v_cvt_pk_bf16_f32 v87, v88, v89
	global_store_dwordx2 v[50:51], v[86:87], off offset:-512
	v_pk_mul_f32 v[84:85], v[20:21], v[118:119]
	v_pk_mul_f32 v[82:83], v[18:19], v[116:117]
	s_nop 0
	v_cvt_pk_bf16_f32 v82, v82, v83
	v_cvt_pk_bf16_f32 v83, v84, v85
	global_store_dwordx2 v[50:51], v[82:83], off
	v_pk_mul_f32 v[88:89], v[24:25], v[122:123]
	v_pk_mul_f32 v[86:87], v[22:23], v[120:121]
	s_nop 0
	v_cvt_pk_bf16_f32 v86, v86, v87
	v_cvt_pk_bf16_f32 v87, v88, v89
	global_store_dwordx2 v[50:51], v[86:87], off offset:512
	v_pk_mul_f32 v[84:85], v[28:29], v[126:127]
	v_pk_mul_f32 v[82:83], v[26:27], v[124:125]
	s_nop 0
	v_cvt_pk_bf16_f32 v82, v82, v83
	v_cvt_pk_bf16_f32 v83, v84, v85
	global_store_dwordx2 v[50:51], v[82:83], off offset:1024
	v_pk_mul_f32 v[88:89], v[32:33], v[130:131]
	v_pk_mul_f32 v[86:87], v[30:31], v[128:129]
	s_nop 0
	v_cvt_pk_bf16_f32 v86, v86, v87
	v_cvt_pk_bf16_f32 v87, v88, v89
	global_store_dwordx2 v[50:51], v[86:87], off offset:1536
	v_lshl_add_u64 v[48:49], v[48:49], 0, s[6:7]
	v_readlane_b32 s6, v254, 43
	v_readlane_b32 s7, v254, 44
	s_nop 1
	v_lshl_add_u64 v[50:51], v[50:51], 0, s[6:7]
	s_andn2_b64 exec, exec, s[4:5]
	s_cbranch_execz .LBB0_393

; #define LAS __attribute__((address_space(3)))
; __device__ __forceinline__ unsigned cvt_pk_bf16(float lo, float hi) { const f32x2 v = {lo, hi}; const bf16v2 r = __builtin_convertvector(v, bf16v2); return __builtin_bit_cast(unsigned, r); }
;     __device__ __forceinline__ void operator()(const f32x4 (&acc)[2][2][4][2], const Unit& u, int wr, int wc, int fr, int fq) const {
;         const int row0 = u.pm * BM + wr * 64 + fr, col0 = u.pn * BM + wc * 32 + 4 * fq;
;         LAS float* part = (LAS float*)(lds + LDS_PART);
;         f32x4 gv[2][2];
;         if (gain) {
; #pragma unroll
;             for (int bj = 0; bj < 2; ++bj)
; #pragma unroll
;                 for (int n = 0; n < 2; ++n) gv[bj][n] = *(const f32x4*)(gain + col0 + bj * HALF + n * 16);
;         }
; #pragma unroll
;         for (int aim = 0; aim < 4; ++aim) { const int ai = aim >> 1;
;             f32x4 res[4][2][2];
; #pragma unroll
;             for (int m = (aim & 1) * 2; m < (aim & 1) * 2 + 2; ++m)
; #pragma unroll
;                 for (int bj = 0; bj < 2; ++bj)
; #pragma unroll
;                     for (int n = 0; n < 2; ++n) res[m][bj][n] = *(const f32x4*)(C + (size_t)(row0 + ai * HALF + m * 16) * ldc + col0 + bj * HALF + n * 16);
; #pragma unroll
;             for (int m = (aim & 1) * 2; m < (aim & 1) * 2 + 2; ++m) { const int row = row0 + ai * HALF + m * 16; float* rowp = C + (size_t)row * ldc + col0; float sq = 0.f;
; #pragma unroll
;                 for (int bj = 0; bj < 2; ++bj)
; #pragma unroll
;                     for (int n = 0; n < 2; ++n) { f32x4* p = (f32x4*)(rowp + bj * HALF + n * 16); const f32x4 x = res[m][bj][n] + acc[ai][bj][m][n] * scale; *p = x;
;                         if (gain) { sq += x[0] * x[0] + x[1] * x[1] + x[2] * x[2] + x[3] * x[3]; const f32x4 y = x * gv[bj][n];
;                             u32x2 w; w.x = cvt_pk_bf16(y[0], y[1]); w.y = cvt_pk_bf16(y[2], y[3]); *(u32x2*)(XG + (size_t)row * ldc + col0 + bj * HALF + n * 16) = w; } }
;                 if (gain) { sq += __shfl_xor(sq, 16); sq += __shfl_xor(sq, 32); if (fq == 0) part[wc * 256 + ai * HALF + wr * 64 + m * 16 + fr] = sq; } }
.Lepi1_fast:
	s_mov_b64 s[44:45], s[4:5]
	s_cmp_lg_u32 s19, 2
	s_cbranch_scc1 .Lepi1_base_done
	v_readlane_b32 s44, v254, 45
	v_readlane_b32 s45, v254, 46
	s_cmp_lt_u32 s48, 0x2000
	s_cbranch_scc1 .Lepi1_base_done
	v_readlane_b32 s44, v254, 47
	v_readlane_b32 s45, v254, 48
	s_nop 3
	s_sub_u32 s44, s44, 0x4000000
	s_subb_u32 s45, s45, 0
.Lepi1_base_done:
	s_nop 3
	v_lshl_or_b32 v206, s63, 8, v233
	v_add_u32_e32 v0, s48, v235
	v_lshlrev_b32_e32 v178, 13, v0
	v_lshl_add_u32 v178, v206, 2, v178
	v_lshlrev_b32_e32 v0, 2, v206
	v_lshrrev_b32_e32 v179, 1, v178
	global_load_dwordx4 v[130:133], v0, s[20:21] offset:0
	global_load_dwordx4 v[134:137], v0, s[20:21] offset:64
	global_load_dwordx4 v[138:141], v0, s[20:21] offset:512
	global_load_dwordx4 v[142:145], v0, s[20:21] offset:576
	s_add_u32 s0, s44, 0x0
	s_addc_u32 s1, s45, 0
	global_load_dwordx4 v[146:149], v178, s[0:1] offset:0
	global_load_dwordx4 v[150:153], v178, s[0:1] offset:64
	global_load_dwordx4 v[154:157], v178, s[0:1] offset:512
	global_load_dwordx4 v[158:161], v178, s[0:1] offset:576
	s_add_u32 s0, s44, 0x20000
	s_addc_u32 s1, s45, 0
	global_load_dwordx4 v[162:165], v178, s[0:1] offset:0
	global_load_dwordx4 v[166:169], v178, s[0:1] offset:64
	global_load_dwordx4 v[170:173], v178, s[0:1] offset:512
	global_load_dwordx4 v[174:177], v178, s[0:1] offset:576
	s_add_u32 s0, s44, 0x40000
	s_addc_u32 s1, s45, 0
	global_load_dwordx4 v[206:209], v178, s[0:1] offset:0
	global_load_dwordx4 v[210:213], v178, s[0:1] offset:64
	global_load_dwordx4 v[214:217], v178, s[0:1] offset:512
	global_load_dwordx4 v[218:221], v178, s[0:1] offset:576
	v_xor_b32_e32 v180, 16, v229
	v_xor_b32_e32 v181, 32, v229
	v_lshlrev_b32_e32 v180, 2, v180
	v_lshlrev_b32_e32 v181, 2, v181
	s_waitcnt vmcnt(8)
	v_pk_fma_f32 v[126:127], s[22:23], v[126:127], v[146:147]
	v_pk_fma_f32 v[128:129], s[22:23], v[128:129], v[148:149]
	v_pk_fma_f32 v[122:123], s[22:23], v[122:123], v[150:151]
	v_pk_fma_f32 v[124:125], s[22:23], v[124:125], v[152:153]
	v_pk_fma_f32 v[94:95], s[22:23], v[94:95], v[154:155]
	v_pk_fma_f32 v[96:97], s[22:23], v[96:97], v[156:157]
	v_pk_fma_f32 v[90:91], s[22:23], v[90:91], v[158:159]
	v_pk_fma_f32 v[92:93], s[22:23], v[92:93], v[160:161]
	s_add_u32 s0, s44, 0x60000
	s_addc_u32 s1, s45, 0
	global_load_dwordx4 v[146:149], v178, s[0:1] offset:0
	global_load_dwordx4 v[150:153], v178, s[0:1] offset:64
	global_load_dwordx4 v[154:157], v178, s[0:1] offset:512
	global_load_dwordx4 v[158:161], v178, s[0:1] offset:576
	s_add_u32 s0, s4, 0x0
	s_addc_u32 s1, s5, 0
	s_add_u32 s12, s14, 0x0
	s_addc_u32 s13, s15, 0
	global_store_dwordx4 v178, v[126:129], s[0:1] offset:0
	global_store_dwordx4 v178, v[122:125], s[0:1] offset:64
	global_store_dwordx4 v178, v[94:97], s[0:1] offset:512
	global_store_dwordx4 v178, v[90:93], s[0:1] offset:576
	v_pk_mul_f32 v[222:223], v[130:131], v[126:127]
	v_pk_mul_f32 v[224:225], v[132:133], v[128:129]
	v_cvt_pk_bf16_f32 v182, v222, v223
	v_cvt_pk_bf16_f32 v183, v224, v225
	global_store_dwordx2 v179, v[182:183], s[12:13] offset:0
	v_pk_mul_f32 v[222:223], v[134:135], v[122:123]
	v_pk_mul_f32 v[224:225], v[136:137], v[124:125]
	v_cvt_pk_bf16_f32 v184, v222, v223
	v_cvt_pk_bf16_f32 v185, v224, v225
	global_store_dwordx2 v179, v[184:185], s[12:13] offset:32
	v_pk_mul_f32 v[222:223], v[138:139], v[94:95]
	v_pk_mul_f32 v[224:225], v[140:141], v[96:97]
	v_cvt_pk_bf16_f32 v182, v222, v223
	v_cvt_pk_bf16_f32 v183, v224, v225
	global_store_dwordx2 v179, v[182:183], s[12:13] offset:256
	v_pk_mul_f32 v[222:223], v[142:143], v[90:91]
	v_pk_mul_f32 v[224:225], v[144:145], v[92:93]
	v_cvt_pk_bf16_f32 v184, v222, v223
	v_cvt_pk_bf16_f32 v185, v224, v225
	global_store_dwordx2 v179, v[184:185], s[12:13] offset:288
	v_mul_f32_e32 v186, v126, v126
	v_fmac_f32_e32 v186, v127, v127
	v_fmac_f32_e32 v186, v128, v128
	v_fmac_f32_e32 v186, v129, v129
	v_fmac_f32_e32 v186, v122, v122
	v_fmac_f32_e32 v186, v123, v123
	v_fmac_f32_e32 v186, v124, v124
	v_fmac_f32_e32 v186, v125, v125
	v_fmac_f32_e32 v186, v94, v94
	v_fmac_f32_e32 v186, v95, v95
	v_fmac_f32_e32 v186, v96, v96
	v_fmac_f32_e32 v186, v97, v97
	v_fmac_f32_e32 v186, v90, v90
	v_fmac_f32_e32 v186, v91, v91
	v_fmac_f32_e32 v186, v92, v92
	v_fmac_f32_e32 v186, v93, v93
	s_nop 0
	v_mov_b32_e32 v126, v186
	s_waitcnt vmcnt(16)
	v_pk_fma_f32 v[118:119], s[22:23], v[118:119], v[162:163]
	v_pk_fma_f32 v[120:121], s[22:23], v[120:121], v[164:165]
	v_pk_fma_f32 v[114:115], s[22:23], v[114:115], v[166:167]
	v_pk_fma_f32 v[116:117], s[22:23], v[116:117], v[168:169]
	v_pk_fma_f32 v[86:87], s[22:23], v[86:87], v[170:171]
	v_pk_fma_f32 v[88:89], s[22:23], v[88:89], v[172:173]
	v_pk_fma_f32 v[82:83], s[22:23], v[82:83], v[174:175]
	v_pk_fma_f32 v[84:85], s[22:23], v[84:85], v[176:177]
	s_add_u32 s0, s44, 0x100000
	s_addc_u32 s1, s45, 0
	global_load_dwordx4 v[162:165], v178, s[0:1] offset:0
	global_load_dwordx4 v[166:169], v178, s[0:1] offset:64
	global_load_dwordx4 v[170:173], v178, s[0:1] offset:512
	global_load_dwordx4 v[174:177], v178, s[0:1] offset:576
	s_add_u32 s0, s4, 0x20000
	s_addc_u32 s1, s5, 0
	s_add_u32 s12, s14, 0x10000
	s_addc_u32 s13, s15, 0
	global_store_dwordx4 v178, v[118:121], s[0:1] offset:0
	global_store_dwordx4 v178, v[114:117], s[0:1] offset:64
	global_store_dwordx4 v178, v[86:89], s[0:1] offset:512
	global_store_dwordx4 v178, v[82:85], s[0:1] offset:576
	v_pk_mul_f32 v[222:223], v[130:131], v[118:119]
	v_pk_mul_f32 v[224:225], v[132:133], v[120:121]
	v_cvt_pk_bf16_f32 v182, v222, v223
	v_cvt_pk_bf16_f32 v183, v224, v225
	global_store_dwordx2 v179, v[182:183], s[12:13] offset:0
	v_pk_mul_f32 v[222:223], v[134:135], v[114:115]
	v_pk_mul_f32 v[224:225], v[136:137], v[116:117]
	v_cvt_pk_bf16_f32 v184, v222, v223
	v_cvt_pk_bf16_f32 v185, v224, v225
	global_store_dwordx2 v179, v[184:185], s[12:13] offset:32
	v_pk_mul_f32 v[222:223], v[138:139], v[86:87]
	v_pk_mul_f32 v[224:225], v[140:141], v[88:89]
	v_cvt_pk_bf16_f32 v182, v222, v223
	v_cvt_pk_bf16_f32 v183, v224, v225
	global_store_dwordx2 v179, v[182:183], s[12:13] offset:256
	v_pk_mul_f32 v[222:223], v[142:143], v[82:83]
	v_pk_mul_f32 v[224:225], v[144:145], v[84:85]
	v_cvt_pk_bf16_f32 v184, v222, v223
	v_cvt_pk_bf16_f32 v185, v224, v225
	global_store_dwordx2 v179, v[184:185], s[12:13] offset:288
	v_mul_f32_e32 v186, v118, v118
	v_fmac_f32_e32 v186, v119, v119
	v_fmac_f32_e32 v186, v120, v120
	v_fmac_f32_e32 v186, v121, v121
	v_fmac_f32_e32 v186, v114, v114
	v_fmac_f32_e32 v186, v115, v115
	v_fmac_f32_e32 v186, v116, v116
	v_fmac_f32_e32 v186, v117, v117
	v_fmac_f32_e32 v186, v86, v86
	v_fmac_f32_e32 v186, v87, v87
	v_fmac_f32_e32 v186, v88, v88
	v_fmac_f32_e32 v186, v89, v89
	v_fmac_f32_e32 v186, v82, v82
	v_fmac_f32_e32 v186, v83, v83
	v_fmac_f32_e32 v186, v84, v84
	v_fmac_f32_e32 v186, v85, v85
	s_nop 0
	v_mov_b32_e32 v118, v186
	s_waitcnt vmcnt(24)
; __device__ __forceinline__ unsigned cvt_pk_bf16(float lo, float hi) { const f32x2 v = {lo, hi}; const bf16v2 r = __builtin_convertvector(v, bf16v2); return __builtin_bit_cast(unsigned, r); }
;     __device__ __forceinline__ void operator()(const f32x4 (&acc)[2][2][4][2], const Unit& u, int wr, int wc, int fr, int fq) const {
;     ...
;                 for (int n = 0; n < 2; ++n) gv[bj][n] = *(const f32x4*)(gain + col0 + bj * HALF + n * 16);
;         }
; #pragma unroll
;         for (int aim = 0; aim < 4; ++aim) { const int ai = aim >> 1;
;             f32x4 res[4][2][2];
; #pragma unroll
;             for (int m = (aim & 1) * 2; m < (aim & 1) * 2 + 2; ++m)
; #pragma unroll
;                 for (int bj = 0; bj < 2; ++bj)
; #pragma unroll
;                     for (int n = 0; n < 2; ++n) res[m][bj][n] = *(const f32x4*)(C + (size_t)(row0 + ai * HALF + m * 16) * ldc + col0 + bj * HALF + n * 16);
; #pragma unroll
;             for (int m = (aim & 1) * 2; m < (aim & 1) * 2 + 2; ++m) { const int row = row0 + ai * HALF + m * 16; float* rowp = C + (size_t)row * ldc + col0; float sq = 0.f;
; #pragma unroll
;                 for (int bj = 0; bj < 2; ++bj)
; #pragma unroll
;                     for (int n = 0; n < 2; ++n) { f32x4* p = (f32x4*)(rowp + bj * HALF + n * 16); const f32x4 x = res[m][bj][n] + acc[ai][bj][m][n] * scale; *p = x;
;                         if (gain) { sq += x[0] * x[0] + x[1] * x[1] + x[2] * x[2] + x[3] * x[3]; const f32x4 y = x * gv[bj][n];
;                             u32x2 w; w.x = cvt_pk_bf16(y[0], y[1]); w.y = cvt_pk_bf16(y[2], y[3]); *(u32x2*)(XG + (size_t)row * ldc + col0 + bj * HALF + n * 16) = w; } }
;                 if (gain) { sq += __shfl_xor(sq, 16); sq += __shfl_xor(sq, 32); if (fq == 0) part[wc * 256 + ai * HALF + wr * 64 + m * 16 + fr] = sq; } }
	v_pk_fma_f32 v[110:111], s[22:23], v[110:111], v[206:207]
	v_pk_fma_f32 v[112:113], s[22:23], v[112:113], v[208:209]
	v_pk_fma_f32 v[106:107], s[22:23], v[106:107], v[210:211]
	v_pk_fma_f32 v[108:109], s[22:23], v[108:109], v[212:213]
	v_pk_fma_f32 v[78:79], s[22:23], v[78:79], v[214:215]
	v_pk_fma_f32 v[80:81], s[22:23], v[80:81], v[216:217]
	v_pk_fma_f32 v[74:75], s[22:23], v[74:75], v[218:219]
	v_pk_fma_f32 v[76:77], s[22:23], v[76:77], v[220:221]
	s_add_u32 s0, s44, 0x120000
	s_addc_u32 s1, s45, 0
	global_load_dwordx4 v[206:209], v178, s[0:1] offset:0
	global_load_dwordx4 v[210:213], v178, s[0:1] offset:64
	global_load_dwordx4 v[214:217], v178, s[0:1] offset:512
	global_load_dwordx4 v[218:221], v178, s[0:1] offset:576
	s_add_u32 s0, s4, 0x40000
	s_addc_u32 s1, s5, 0
	s_add_u32 s12, s14, 0x20000
	s_addc_u32 s13, s15, 0
	global_store_dwordx4 v178, v[110:113], s[0:1] offset:0
	global_store_dwordx4 v178, v[106:109], s[0:1] offset:64
	global_store_dwordx4 v178, v[78:81], s[0:1] offset:512
	global_store_dwordx4 v178, v[74:77], s[0:1] offset:576
	v_pk_mul_f32 v[222:223], v[130:131], v[110:111]
	v_pk_mul_f32 v[224:225], v[132:133], v[112:113]
	v_cvt_pk_bf16_f32 v182, v222, v223
	v_cvt_pk_bf16_f32 v183, v224, v225
	global_store_dwordx2 v179, v[182:183], s[12:13] offset:0
	v_pk_mul_f32 v[222:223], v[134:135], v[106:107]
	v_pk_mul_f32 v[224:225], v[136:137], v[108:109]
	v_cvt_pk_bf16_f32 v184, v222, v223
	v_cvt_pk_bf16_f32 v185, v224, v225
	global_store_dwordx2 v179, v[184:185], s[12:13] offset:32
	v_pk_mul_f32 v[222:223], v[138:139], v[78:79]
	v_pk_mul_f32 v[224:225], v[140:141], v[80:81]
	v_cvt_pk_bf16_f32 v182, v222, v223
	v_cvt_pk_bf16_f32 v183, v224, v225
	global_store_dwordx2 v179, v[182:183], s[12:13] offset:256
	v_pk_mul_f32 v[222:223], v[142:143], v[74:75]
	v_pk_mul_f32 v[224:225], v[144:145], v[76:77]
	v_cvt_pk_bf16_f32 v184, v222, v223
	v_cvt_pk_bf16_f32 v185, v224, v225
	global_store_dwordx2 v179, v[184:185], s[12:13] offset:288
	v_mul_f32_e32 v186, v110, v110
	v_fmac_f32_e32 v186, v111, v111
	v_fmac_f32_e32 v186, v112, v112
	v_fmac_f32_e32 v186, v113, v113
	v_fmac_f32_e32 v186, v106, v106
	v_fmac_f32_e32 v186, v107, v107
	v_fmac_f32_e32 v186, v108, v108
	v_fmac_f32_e32 v186, v109, v109
	v_fmac_f32_e32 v186, v78, v78
	v_fmac_f32_e32 v186, v79, v79
	v_fmac_f32_e32 v186, v80, v80
	v_fmac_f32_e32 v186, v81, v81
	v_fmac_f32_e32 v186, v74, v74
	v_fmac_f32_e32 v186, v75, v75
	v_fmac_f32_e32 v186, v76, v76
	v_fmac_f32_e32 v186, v77, v77
	s_nop 0
	v_mov_b32_e32 v110, v186
	s_waitcnt vmcnt(32)
	v_pk_fma_f32 v[102:103], s[22:23], v[102:103], v[146:147]
	v_pk_fma_f32 v[104:105], s[22:23], v[104:105], v[148:149]
	v_pk_fma_f32 v[98:99], s[22:23], v[98:99], v[150:151]
	v_pk_fma_f32 v[100:101], s[22:23], v[100:101], v[152:153]
	v_pk_fma_f32 v[70:71], s[22:23], v[70:71], v[154:155]
	v_pk_fma_f32 v[72:73], s[22:23], v[72:73], v[156:157]
	v_pk_fma_f32 v[66:67], s[22:23], v[66:67], v[158:159]
	v_pk_fma_f32 v[68:69], s[22:23], v[68:69], v[160:161]
	s_add_u32 s0, s44, 0x140000
	s_addc_u32 s1, s45, 0
	global_load_dwordx4 v[146:149], v178, s[0:1] offset:0
	global_load_dwordx4 v[150:153], v178, s[0:1] offset:64
	global_load_dwordx4 v[154:157], v178, s[0:1] offset:512
	global_load_dwordx4 v[158:161], v178, s[0:1] offset:576
	s_add_u32 s0, s4, 0x60000
	s_addc_u32 s1, s5, 0
	s_add_u32 s12, s14, 0x30000
	s_addc_u32 s13, s15, 0
	global_store_dwordx4 v178, v[102:105], s[0:1] offset:0
	global_store_dwordx4 v178, v[98:101], s[0:1] offset:64
	global_store_dwordx4 v178, v[70:73], s[0:1] offset:512
	global_store_dwordx4 v178, v[66:69], s[0:1] offset:576
	v_pk_mul_f32 v[222:223], v[130:131], v[102:103]
	v_pk_mul_f32 v[224:225], v[132:133], v[104:105]
	v_cvt_pk_bf16_f32 v182, v222, v223
	v_cvt_pk_bf16_f32 v183, v224, v225
	global_store_dwordx2 v179, v[182:183], s[12:13] offset:0
	v_pk_mul_f32 v[222:223], v[134:135], v[98:99]
	v_pk_mul_f32 v[224:225], v[136:137], v[100:101]
	v_cvt_pk_bf16_f32 v184, v222, v223
	v_cvt_pk_bf16_f32 v185, v224, v225
	global_store_dwordx2 v179, v[184:185], s[12:13] offset:32
	v_pk_mul_f32 v[222:223], v[138:139], v[70:71]
	v_pk_mul_f32 v[224:225], v[140:141], v[72:73]
	v_cvt_pk_bf16_f32 v182, v222, v223
	v_cvt_pk_bf16_f32 v183, v224, v225
	global_store_dwordx2 v179, v[182:183], s[12:13] offset:256
	v_pk_mul_f32 v[222:223], v[142:143], v[66:67]
	v_pk_mul_f32 v[224:225], v[144:145], v[68:69]
	v_cvt_pk_bf16_f32 v184, v222, v223
	v_cvt_pk_bf16_f32 v185, v224, v225
	global_store_dwordx2 v179, v[184:185], s[12:13] offset:288
	v_mul_f32_e32 v186, v102, v102
	v_fmac_f32_e32 v186, v103, v103
	v_fmac_f32_e32 v186, v104, v104
	v_fmac_f32_e32 v186, v105, v105
	v_fmac_f32_e32 v186, v98, v98
	v_fmac_f32_e32 v186, v99, v99
	v_fmac_f32_e32 v186, v100, v100
	v_fmac_f32_e32 v186, v101, v101
	v_fmac_f32_e32 v186, v70, v70
	v_fmac_f32_e32 v186, v71, v71
	v_fmac_f32_e32 v186, v72, v72
	v_fmac_f32_e32 v186, v73, v73
	v_fmac_f32_e32 v186, v66, v66
	v_fmac_f32_e32 v186, v67, v67
	v_fmac_f32_e32 v186, v68, v68
	v_fmac_f32_e32 v186, v69, v69
	s_nop 0
	v_mov_b32_e32 v102, v186
	s_waitcnt vmcnt(32)
; __device__ __forceinline__ unsigned cvt_pk_bf16(float lo, float hi) { const f32x2 v = {lo, hi}; const bf16v2 r = __builtin_convertvector(v, bf16v2); return __builtin_bit_cast(unsigned, r); }
;     __device__ __forceinline__ void operator()(const f32x4 (&acc)[2][2][4][2], const Unit& u, int wr, int wc, int fr, int fq) const {
;     ...
;         for (int aim = 0; aim < 4; ++aim) { const int ai = aim >> 1;
;             f32x4 res[4][2][2];
; #pragma unroll
;             for (int m = (aim & 1) * 2; m < (aim & 1) * 2 + 2; ++m)
; #pragma unroll
;                 for (int bj = 0; bj < 2; ++bj)
; #pragma unroll
;                     for (int n = 0; n < 2; ++n) res[m][bj][n] = *(const f32x4*)(C + (size_t)(row0 + ai * HALF + m * 16) * ldc + col0 + bj * HALF + n * 16);
; #pragma unroll
;             for (int m = (aim & 1) * 2; m < (aim & 1) * 2 + 2; ++m) { const int row = row0 + ai * HALF + m * 16; float* rowp = C + (size_t)row * ldc + col0; float sq = 0.f;
; #pragma unroll
;                 for (int bj = 0; bj < 2; ++bj)
; #pragma unroll
;                     for (int n = 0; n < 2; ++n) { f32x4* p = (f32x4*)(rowp + bj * HALF + n * 16); const f32x4 x = res[m][bj][n] + acc[ai][bj][m][n] * scale; *p = x;
;                         if (gain) { sq += x[0] * x[0] + x[1] * x[1] + x[2] * x[2] + x[3] * x[3]; const f32x4 y = x * gv[bj][n];
;                             u32x2 w; w.x = cvt_pk_bf16(y[0], y[1]); w.y = cvt_pk_bf16(y[2], y[3]); *(u32x2*)(XG + (size_t)row * ldc + col0 + bj * HALF + n * 16) = w; } }
;                 if (gain) { sq += __shfl_xor(sq, 16); sq += __shfl_xor(sq, 32); if (fq == 0) part[wc * 256 + ai * HALF + wr * 64 + m * 16 + fr] = sq; } }
	v_pk_fma_f32 v[62:63], s[22:23], v[62:63], v[162:163]
	v_pk_fma_f32 v[64:65], s[22:23], v[64:65], v[164:165]
	v_pk_fma_f32 v[58:59], s[22:23], v[58:59], v[166:167]
	v_pk_fma_f32 v[60:61], s[22:23], v[60:61], v[168:169]
	v_pk_fma_f32 v[30:31], s[22:23], v[30:31], v[170:171]
	v_pk_fma_f32 v[32:33], s[22:23], v[32:33], v[172:173]
	v_pk_fma_f32 v[26:27], s[22:23], v[26:27], v[174:175]
	v_pk_fma_f32 v[28:29], s[22:23], v[28:29], v[176:177]
	s_add_u32 s0, s44, 0x160000
	s_addc_u32 s1, s45, 0
	global_load_dwordx4 v[162:165], v178, s[0:1] offset:0
	global_load_dwordx4 v[166:169], v178, s[0:1] offset:64
	global_load_dwordx4 v[170:173], v178, s[0:1] offset:512
	global_load_dwordx4 v[174:177], v178, s[0:1] offset:576
	s_add_u32 s0, s4, 0x100000
	s_addc_u32 s1, s5, 0
	s_add_u32 s12, s14, 0x80000
	s_addc_u32 s13, s15, 0
	global_store_dwordx4 v178, v[62:65], s[0:1] offset:0
	global_store_dwordx4 v178, v[58:61], s[0:1] offset:64
	global_store_dwordx4 v178, v[30:33], s[0:1] offset:512
	global_store_dwordx4 v178, v[26:29], s[0:1] offset:576
	v_pk_mul_f32 v[222:223], v[130:131], v[62:63]
	v_pk_mul_f32 v[224:225], v[132:133], v[64:65]
	v_cvt_pk_bf16_f32 v182, v222, v223
	v_cvt_pk_bf16_f32 v183, v224, v225
	global_store_dwordx2 v179, v[182:183], s[12:13] offset:0
	v_pk_mul_f32 v[222:223], v[134:135], v[58:59]
	v_pk_mul_f32 v[224:225], v[136:137], v[60:61]
	v_cvt_pk_bf16_f32 v184, v222, v223
	v_cvt_pk_bf16_f32 v185, v224, v225
	global_store_dwordx2 v179, v[184:185], s[12:13] offset:32
	v_pk_mul_f32 v[222:223], v[138:139], v[30:31]
	v_pk_mul_f32 v[224:225], v[140:141], v[32:33]
	v_cvt_pk_bf16_f32 v182, v222, v223
	v_cvt_pk_bf16_f32 v183, v224, v225
	global_store_dwordx2 v179, v[182:183], s[12:13] offset:256
	v_pk_mul_f32 v[222:223], v[142:143], v[26:27]
	v_pk_mul_f32 v[224:225], v[144:145], v[28:29]
	v_cvt_pk_bf16_f32 v184, v222, v223
	v_cvt_pk_bf16_f32 v185, v224, v225
	global_store_dwordx2 v179, v[184:185], s[12:13] offset:288
	v_mul_f32_e32 v186, v62, v62
	v_fmac_f32_e32 v186, v63, v63
	v_fmac_f32_e32 v186, v64, v64
	v_fmac_f32_e32 v186, v65, v65
	v_fmac_f32_e32 v186, v58, v58
	v_fmac_f32_e32 v186, v59, v59
	v_fmac_f32_e32 v186, v60, v60
	v_fmac_f32_e32 v186, v61, v61
	v_fmac_f32_e32 v186, v30, v30
	v_fmac_f32_e32 v186, v31, v31
	v_fmac_f32_e32 v186, v32, v32
	v_fmac_f32_e32 v186, v33, v33
	v_fmac_f32_e32 v186, v26, v26
	v_fmac_f32_e32 v186, v27, v27
	v_fmac_f32_e32 v186, v28, v28
	v_fmac_f32_e32 v186, v29, v29
	s_nop 0
	v_mov_b32_e32 v62, v186
	s_waitcnt vmcnt(32)
	v_pk_fma_f32 v[54:55], s[22:23], v[54:55], v[206:207]
	v_pk_fma_f32 v[56:57], s[22:23], v[56:57], v[208:209]
	v_pk_fma_f32 v[50:51], s[22:23], v[50:51], v[210:211]
	v_pk_fma_f32 v[52:53], s[22:23], v[52:53], v[212:213]
	v_pk_fma_f32 v[22:23], s[22:23], v[22:23], v[214:215]
	v_pk_fma_f32 v[24:25], s[22:23], v[24:25], v[216:217]
	v_pk_fma_f32 v[18:19], s[22:23], v[18:19], v[218:219]
	v_pk_fma_f32 v[20:21], s[22:23], v[20:21], v[220:221]
	s_add_u32 s0, s4, 0x120000
	s_addc_u32 s1, s5, 0
	s_add_u32 s12, s14, 0x90000
	s_addc_u32 s13, s15, 0
	global_store_dwordx4 v178, v[54:57], s[0:1] offset:0
	global_store_dwordx4 v178, v[50:53], s[0:1] offset:64
	global_store_dwordx4 v178, v[22:25], s[0:1] offset:512
	global_store_dwordx4 v178, v[18:21], s[0:1] offset:576
	v_pk_mul_f32 v[222:223], v[130:131], v[54:55]
	v_pk_mul_f32 v[224:225], v[132:133], v[56:57]
	v_cvt_pk_bf16_f32 v182, v222, v223
	v_cvt_pk_bf16_f32 v183, v224, v225
	global_store_dwordx2 v179, v[182:183], s[12:13] offset:0
	v_pk_mul_f32 v[222:223], v[134:135], v[50:51]
	v_pk_mul_f32 v[224:225], v[136:137], v[52:53]
	v_cvt_pk_bf16_f32 v184, v222, v223
	v_cvt_pk_bf16_f32 v185, v224, v225
	global_store_dwordx2 v179, v[184:185], s[12:13] offset:32
	v_pk_mul_f32 v[222:223], v[138:139], v[22:23]
	v_pk_mul_f32 v[224:225], v[140:141], v[24:25]
	v_cvt_pk_bf16_f32 v182, v222, v223
	v_cvt_pk_bf16_f32 v183, v224, v225
	global_store_dwordx2 v179, v[182:183], s[12:13] offset:256
	v_pk_mul_f32 v[222:223], v[142:143], v[18:19]
	v_pk_mul_f32 v[224:225], v[144:145], v[20:21]
	v_cvt_pk_bf16_f32 v184, v222, v223
	v_cvt_pk_bf16_f32 v185, v224, v225
	global_store_dwordx2 v179, v[184:185], s[12:13] offset:288
	v_mul_f32_e32 v186, v54, v54
	v_fmac_f32_e32 v186, v55, v55
	v_fmac_f32_e32 v186, v56, v56
	v_fmac_f32_e32 v186, v57, v57
	v_fmac_f32_e32 v186, v50, v50
	v_fmac_f32_e32 v186, v51, v51
	v_fmac_f32_e32 v186, v52, v52
	v_fmac_f32_e32 v186, v53, v53
	v_fmac_f32_e32 v186, v22, v22
	v_fmac_f32_e32 v186, v23, v23
	v_fmac_f32_e32 v186, v24, v24
	v_fmac_f32_e32 v186, v25, v25
	v_fmac_f32_e32 v186, v18, v18
	v_fmac_f32_e32 v186, v19, v19
	v_fmac_f32_e32 v186, v20, v20
	v_fmac_f32_e32 v186, v21, v21
	s_nop 0
	v_mov_b32_e32 v54, v186
	s_waitcnt vmcnt(28)
; __device__ __forceinline__ unsigned cvt_pk_bf16(float lo, float hi) { const f32x2 v = {lo, hi}; const bf16v2 r = __builtin_convertvector(v, bf16v2); return __builtin_bit_cast(unsigned, r); }
;     __device__ __forceinline__ void operator()(const f32x4 (&acc)[2][2][4][2], const Unit& u, int wr, int wc, int fr, int fq) const {
;     ...
;             for (int m = (aim & 1) * 2; m < (aim & 1) * 2 + 2; ++m) { const int row = row0 + ai * HALF + m * 16; float* rowp = C + (size_t)row * ldc + col0; float sq = 0.f;
; #pragma unroll
;                 for (int bj = 0; bj < 2; ++bj)
; #pragma unroll
;                     for (int n = 0; n < 2; ++n) { f32x4* p = (f32x4*)(rowp + bj * HALF + n * 16); const f32x4 x = res[m][bj][n] + acc[ai][bj][m][n] * scale; *p = x;
;                         if (gain) { sq += x[0] * x[0] + x[1] * x[1] + x[2] * x[2] + x[3] * x[3]; const f32x4 y = x * gv[bj][n];
;                             u32x2 w; w.x = cvt_pk_bf16(y[0], y[1]); w.y = cvt_pk_bf16(y[2], y[3]); *(u32x2*)(XG + (size_t)row * ldc + col0 + bj * HALF + n * 16) = w; } }
;                 if (gain) { sq += __shfl_xor(sq, 16); sq += __shfl_xor(sq, 32); if (fq == 0) part[wc * 256 + ai * HALF + wr * 64 + m * 16 + fr] = sq; } }
	v_pk_fma_f32 v[46:47], s[22:23], v[46:47], v[146:147]
	v_pk_fma_f32 v[48:49], s[22:23], v[48:49], v[148:149]
	v_pk_fma_f32 v[42:43], s[22:23], v[42:43], v[150:151]
	v_pk_fma_f32 v[44:45], s[22:23], v[44:45], v[152:153]
	v_pk_fma_f32 v[14:15], s[22:23], v[14:15], v[154:155]
	v_pk_fma_f32 v[16:17], s[22:23], v[16:17], v[156:157]
	v_pk_fma_f32 v[10:11], s[22:23], v[10:11], v[158:159]
	v_pk_fma_f32 v[12:13], s[22:23], v[12:13], v[160:161]
	s_add_u32 s0, s4, 0x140000
	s_addc_u32 s1, s5, 0
	s_add_u32 s12, s14, 0xa0000
	s_addc_u32 s13, s15, 0
	global_store_dwordx4 v178, v[46:49], s[0:1] offset:0
	global_store_dwordx4 v178, v[42:45], s[0:1] offset:64
	global_store_dwordx4 v178, v[14:17], s[0:1] offset:512
	global_store_dwordx4 v178, v[10:13], s[0:1] offset:576
	v_pk_mul_f32 v[222:223], v[130:131], v[46:47]
	v_pk_mul_f32 v[224:225], v[132:133], v[48:49]
	v_cvt_pk_bf16_f32 v182, v222, v223
	v_cvt_pk_bf16_f32 v183, v224, v225
	global_store_dwordx2 v179, v[182:183], s[12:13] offset:0
	v_pk_mul_f32 v[222:223], v[134:135], v[42:43]
	v_pk_mul_f32 v[224:225], v[136:137], v[44:45]
	v_cvt_pk_bf16_f32 v184, v222, v223
	v_cvt_pk_bf16_f32 v185, v224, v225
	global_store_dwordx2 v179, v[184:185], s[12:13] offset:32
	v_pk_mul_f32 v[222:223], v[138:139], v[14:15]
	v_pk_mul_f32 v[224:225], v[140:141], v[16:17]
	v_cvt_pk_bf16_f32 v182, v222, v223
	v_cvt_pk_bf16_f32 v183, v224, v225
	global_store_dwordx2 v179, v[182:183], s[12:13] offset:256
	v_pk_mul_f32 v[222:223], v[142:143], v[10:11]
	v_pk_mul_f32 v[224:225], v[144:145], v[12:13]
	v_cvt_pk_bf16_f32 v184, v222, v223
	v_cvt_pk_bf16_f32 v185, v224, v225
	global_store_dwordx2 v179, v[184:185], s[12:13] offset:288
	v_mul_f32_e32 v186, v46, v46
	v_fmac_f32_e32 v186, v47, v47
	v_fmac_f32_e32 v186, v48, v48
	v_fmac_f32_e32 v186, v49, v49
	v_fmac_f32_e32 v186, v42, v42
	v_fmac_f32_e32 v186, v43, v43
	v_fmac_f32_e32 v186, v44, v44
	v_fmac_f32_e32 v186, v45, v45
	v_fmac_f32_e32 v186, v14, v14
	v_fmac_f32_e32 v186, v15, v15
	v_fmac_f32_e32 v186, v16, v16
	v_fmac_f32_e32 v186, v17, v17
	v_fmac_f32_e32 v186, v10, v10
	v_fmac_f32_e32 v186, v11, v11
	v_fmac_f32_e32 v186, v12, v12
	v_fmac_f32_e32 v186, v13, v13
	s_nop 0
	v_mov_b32_e32 v46, v186
	s_waitcnt vmcnt(24)
	v_pk_fma_f32 v[38:39], s[22:23], v[38:39], v[162:163]
	v_pk_fma_f32 v[40:41], s[22:23], v[40:41], v[164:165]
	v_pk_fma_f32 v[34:35], s[22:23], v[34:35], v[166:167]
	v_pk_fma_f32 v[36:37], s[22:23], v[36:37], v[168:169]
	v_pk_fma_f32 v[6:7], s[22:23], v[6:7], v[170:171]
	v_pk_fma_f32 v[8:9], s[22:23], v[8:9], v[172:173]
	v_pk_fma_f32 v[2:3], s[22:23], v[2:3], v[174:175]
	v_pk_fma_f32 v[4:5], s[22:23], v[4:5], v[176:177]
	s_add_u32 s0, s4, 0x160000
	s_addc_u32 s1, s5, 0
	s_add_u32 s12, s14, 0xb0000
	s_addc_u32 s13, s15, 0
	global_store_dwordx4 v178, v[38:41], s[0:1] offset:0
	global_store_dwordx4 v178, v[34:37], s[0:1] offset:64
	global_store_dwordx4 v178, v[6:9], s[0:1] offset:512
	global_store_dwordx4 v178, v[2:5], s[0:1] offset:576
	v_pk_mul_f32 v[222:223], v[130:131], v[38:39]
	v_pk_mul_f32 v[224:225], v[132:133], v[40:41]
	v_cvt_pk_bf16_f32 v182, v222, v223
	v_cvt_pk_bf16_f32 v183, v224, v225
	global_store_dwordx2 v179, v[182:183], s[12:13] offset:0
	v_pk_mul_f32 v[222:223], v[134:135], v[34:35]
	v_pk_mul_f32 v[224:225], v[136:137], v[36:37]
	v_cvt_pk_bf16_f32 v184, v222, v223
	v_cvt_pk_bf16_f32 v185, v224, v225
	global_store_dwordx2 v179, v[184:185], s[12:13] offset:32
	v_pk_mul_f32 v[222:223], v[138:139], v[6:7]
	v_pk_mul_f32 v[224:225], v[140:141], v[8:9]
	v_cvt_pk_bf16_f32 v182, v222, v223
	v_cvt_pk_bf16_f32 v183, v224, v225
	global_store_dwordx2 v179, v[182:183], s[12:13] offset:256
	v_pk_mul_f32 v[222:223], v[142:143], v[2:3]
	v_pk_mul_f32 v[224:225], v[144:145], v[4:5]
	v_cvt_pk_bf16_f32 v184, v222, v223
	v_cvt_pk_bf16_f32 v185, v224, v225
	global_store_dwordx2 v179, v[184:185], s[12:13] offset:288
	v_mul_f32_e32 v186, v38, v38
	v_fmac_f32_e32 v186, v39, v39
	v_fmac_f32_e32 v186, v40, v40
	v_fmac_f32_e32 v186, v41, v41
	v_fmac_f32_e32 v186, v34, v34
	v_fmac_f32_e32 v186, v35, v35
	v_fmac_f32_e32 v186, v36, v36
	v_fmac_f32_e32 v186, v37, v37
	v_fmac_f32_e32 v186, v6, v6
	v_fmac_f32_e32 v186, v7, v7
	v_fmac_f32_e32 v186, v8, v8
	v_fmac_f32_e32 v186, v9, v9
	v_fmac_f32_e32 v186, v2, v2
	v_fmac_f32_e32 v186, v3, v3
	v_fmac_f32_e32 v186, v4, v4
	v_fmac_f32_e32 v186, v5, v5
	s_nop 0
	v_mov_b32_e32 v38, v186
	ds_bpermute_b32 v127, v180, v126
	ds_bpermute_b32 v119, v180, v118
	ds_bpermute_b32 v111, v180, v110
	ds_bpermute_b32 v103, v180, v102
	ds_bpermute_b32 v63, v180, v62
	ds_bpermute_b32 v55, v180, v54
	ds_bpermute_b32 v47, v180, v46
	ds_bpermute_b32 v39, v180, v38
	s_waitcnt lgkmcnt(0)
	v_add_f32_e32 v126, v126, v127
	v_add_f32_e32 v118, v118, v119
	v_add_f32_e32 v110, v110, v111
	v_add_f32_e32 v102, v102, v103
	v_add_f32_e32 v62, v62, v63
	v_add_f32_e32 v54, v54, v55
	v_add_f32_e32 v46, v46, v47
	v_add_f32_e32 v38, v38, v39
	ds_bpermute_b32 v127, v181, v126
	ds_bpermute_b32 v119, v181, v118
	ds_bpermute_b32 v111, v181, v110
	ds_bpermute_b32 v103, v181, v102
	ds_bpermute_b32 v63, v181, v62
	ds_bpermute_b32 v55, v181, v54
	ds_bpermute_b32 v47, v181, v46
	ds_bpermute_b32 v39, v181, v38
	s_waitcnt lgkmcnt(0)
	v_add_f32_e32 v126, v126, v127
	v_add_f32_e32 v118, v118, v119
	v_add_f32_e32 v110, v110, v111
	v_add_f32_e32 v102, v102, v103
	v_add_f32_e32 v62, v62, v63
	v_add_f32_e32 v54, v54, v55
	v_add_f32_e32 v46, v46, v47
	v_add_f32_e32 v38, v38, v39
	s_and_saveexec_b64 s[44:45], s[38:39]
	ds_write_b32 v231, v126 offset:0
	ds_write_b32 v231, v118 offset:64
	ds_write_b32 v231, v110 offset:128
	ds_write_b32 v231, v102 offset:192
	ds_write_b32 v231, v62 offset:512
	ds_write_b32 v231, v54 offset:576
	ds_write_b32 v231, v46 offset:640
	ds_write_b32 v231, v38 offset:704
	s_or_b64 exec, exec, s[44:45]
	s_branch .Lepi1_join
